# v25 + sample gate gamma/beta hoist + reduce-phase late-load hoist (7/11/16) + phase-12 early c1/c2 loads
# speedup vs baseline: 1.0109x; 1.0109x over previous
; #define LAS __attribute__((address_space(3)))
; #define GASP __attribute__((address_space(1)))
; __device__ __forceinline__ void gate_unit(const Params& p, LAS unsigned char* L, int row0, int n, int g, int sample_b) {
;     ...
;     if (ldr) {
;         float s = 0.f, q = 0.f;
; #pragma unroll
;         for (int i = 0; i < 4; ++i) { s += sp[i][0] + sp[i][2]; q += sp[i][1] + sp[i][3]; }
;         const float mean = s * (1.f / 512.f), rstd = 1.f / sqrtf(q * (1.f / 512.f) - mean * mean + LN_EPS);
;         const float* gp = lng + g * 128 + ch * 32; const float* bp = lnb + g * 128 + ch * 32;
; #pragma unroll
;         for (int i = 0; i < 4; ++i) {
;             const f32x4 ya = (xv[2 * i] - mean) * rstd * *(const GASP f32x4*)(gp + 8 * i) + *(const GASP f32x4*)(bp + 8 * i);
;             const f32x4 yc = (xv[2 * i + 1] - mean) * rstd * *(const GASP f32x4*)(gp + 8 * i + 4) + *(const GASP f32x4*)(bp + 8 * i + 4);
;             u32x4 w; w.x = pk2(ya[0], ya[1]); w.y = pk2(ya[2], ya[3]); w.z = pk2(yc[0], yc[1]); w.w = pk2(yc[2], yc[3]);
;             *(LAS u32x4*)(L + t * DA_VRS + ch * 64 + i * 16) = w;
;             if (sample_b >= 0) { float* o = p.out + OUT_GV + (size_t)(sample_b * 32 + t) * 512 + g * 128 + ch * 32 + 8 * i; *(GASP f32x4*)o = ya; *(GASP f32x4*)(o + 4) = yc; }
.LBB0_885:
	v_mov_b32_e32 v59, v1
	v_readlane_b32 s8, v252, 10
	v_lshlrev_b64 v[106:107], 2, v[58:59]
	v_readlane_b32 s9, v252, 11
	v_mov_b32_e32 v75, v1
	v_lshl_add_u64 v[82:83], s[18:19], 0, v[106:107]
	v_lshl_add_u64 v[84:85], s[8:9], 0, v[106:107]
	v_lshl_add_u64 v[84:85], v[84:85], 0, v[74:75]
	v_lshl_add_u64 v[82:83], v[82:83], 0, v[74:75]
	global_load_dwordx4 v[90:93], v[84:85], off
	global_load_dwordx4 v[94:97], v[82:83], off
	global_load_dwordx4 v[98:101], v[82:83], off offset:16
	global_load_dwordx4 v[102:105], v[84:85], off offset:16
	global_load_dwordx4 v[112:115], v[84:85], off offset:32
	global_load_dwordx4 v[116:119], v[82:83], off offset:32
	global_load_dwordx4 v[120:123], v[82:83], off offset:48
	global_load_dwordx4 v[124:127], v[84:85], off offset:48
	global_load_dwordx4 v[128:131], v[84:85], off offset:64
	global_load_dwordx4 v[132:135], v[82:83], off offset:64
	global_load_dwordx4 v[136:139], v[82:83], off offset:80
	global_load_dwordx4 v[140:143], v[84:85], off offset:80
	global_load_dwordx4 v[144:147], v[84:85], off offset:96
	global_load_dwordx4 v[148:151], v[82:83], off offset:96
	global_load_dwordx4 v[152:155], v[82:83], off offset:112
	global_load_dwordx4 v[156:159], v[84:85], off offset:112
	s_waitcnt vmcnt(16)
	v_pk_add_f32 v[54:55], v[54:55], v[56:57]
	v_pk_add_f32 v[50:51], v[50:51], v[52:53]
	v_pk_add_f32 v[42:43], v[42:43], v[44:45]
	v_pk_add_f32 v[44:45], v[54:55], 0 op_sel_hi:[1,0]
	v_pk_add_f32 v[46:47], v[46:47], v[48:49]
	v_pk_add_f32 v[44:45], v[50:51], v[44:45]
	s_addk_i32 s15, 0xe000
	v_pk_add_f32 v[44:45], v[46:47], v[44:45]
	v_add_u32_e32 v48, s15, v86
	v_pk_add_f32 v[42:43], v[42:43], v[44:45]
	s_mov_b32 s8, 0x3b000000
	v_ashrrev_i32_e32 v49, 31, v48
	v_pk_mul_f32 v[110:111], v[42:43], s[8:9] op_sel_hi:[1,0]
	v_lshlrev_b64 v[108:109], 11, v[48:49]
	v_fma_f32 v0, -v110, v110, v111
	v_lshl_add_u64 v[44:45], s[68:69], 0, v[108:109]
	v_add_f32_e32 v0, 0x3727c5ac, v0
	v_lshl_add_u64 v[42:43], v[44:45], 0, v[106:107]
	v_mul_f32_e32 v44, 0x4f800000, v0
	v_cmp_gt_f32_e32 vcc, s35, v0
	v_sub_f32_e32 v41, v41, v110
	v_sub_f32_e32 v40, v40, v110
	v_cndmask_b32_e32 v0, v0, v44, vcc
	v_sqrt_f32_e32 v44, v0
	v_sub_f32_e32 v39, v39, v110
	v_sub_f32_e32 v38, v38, v110
	v_sub_f32_e32 v33, v33, v110
	v_add_u32_e32 v45, -1, v44
	v_add_u32_e32 v46, 1, v44
	v_fma_f32 v47, -v45, v44, v0
	v_fma_f32 v48, -v46, v44, v0
	v_cmp_ge_f32_e64 s[8:9], 0, v47
	v_sub_f32_e32 v32, v32, v110
	v_sub_f32_e32 v31, v31, v110
	v_cndmask_b32_e64 v44, v44, v45, s[8:9]
	v_cmp_lt_f32_e64 s[8:9], 0, v48
	v_sub_f32_e32 v30, v30, v110
	v_lshl_add_u64 v[42:43], v[42:43], 0, v[74:75]
	v_cndmask_b32_e64 v44, v44, v46, s[8:9]
	v_mul_f32_e32 v45, 0x37800000, v44
	v_cndmask_b32_e32 v44, v44, v45, vcc
	v_cmp_class_f32_e32 vcc, v0, v170
	v_sub_f32_e32 v27, v27, v110
	v_sub_f32_e32 v26, v26, v110
	v_cndmask_b32_e32 v0, v44, v0, vcc
	v_div_scale_f32 v44, s[8:9], v0, v0, 1.0
	v_rcp_f32_e32 v45, v44
	v_div_scale_f32 v46, vcc, 1.0, v0, 1.0
	s_mov_b32 s8, 0x12800000
	v_fma_f32 v47, -v44, v45, 1.0
	v_fmac_f32_e32 v45, v47, v45
	v_mul_f32_e32 v47, v46, v45
	v_fma_f32 v48, -v44, v47, v46
	v_fmac_f32_e32 v47, v48, v45
	v_fma_f32 v44, -v44, v47, v46
	v_div_fmas_f32 v44, v44, v45, v47
	v_div_fixup_f32 v0, v44, v0, 1.0
	v_pk_mul_f32 v[38:39], v[38:39], v[0:1] op_sel_hi:[1,0]
	v_pk_mul_f32 v[40:41], v[40:41], v[0:1] op_sel_hi:[1,0]
	v_pk_mul_f32 v[44:45], v[30:31], v[0:1] op_sel_hi:[1,0]
	v_pk_mul_f32 v[46:47], v[32:33], v[0:1] op_sel_hi:[1,0]
	v_sub_f32_e32 v29, v29, v110
	v_sub_f32_e32 v28, v28, v110
	v_sub_f32_e32 v23, v23, v110
	v_sub_f32_e32 v22, v22, v110
	v_sub_f32_e32 v25, v25, v110
	v_sub_f32_e32 v24, v24, v110
	v_pk_mul_f32 v[28:29], v[28:29], v[0:1] op_sel_hi:[1,0]
	v_pk_mul_f32 v[26:27], v[26:27], v[0:1] op_sel_hi:[1,0]
	v_sub_f32_e32 v19, v19, v110
	v_sub_f32_e32 v18, v18, v110
	v_sub_f32_e32 v21, v21, v110
	v_sub_f32_e32 v20, v20, v110
	v_sub_f32_e32 v11, v11, v110
	v_sub_f32_e32 v10, v10, v110
	s_waitcnt vmcnt(14)
; #define LAS __attribute__((address_space(3)))
; #define GASP __attribute__((address_space(1)))
; __device__ __forceinline__ void gate_unit(const Params& p, LAS unsigned char* L, int row0, int n, int g, int sample_b) {
;     ...
;         for (int i = 0; i < 4; ++i) {
;             const f32x4 ya = (xv[2 * i] - mean) * rstd * *(const GASP f32x4*)(gp + 8 * i) + *(const GASP f32x4*)(bp + 8 * i);
;             const f32x4 yc = (xv[2 * i + 1] - mean) * rstd * *(const GASP f32x4*)(gp + 8 * i + 4) + *(const GASP f32x4*)(bp + 8 * i + 4);
;             u32x4 w; w.x = pk2(ya[0], ya[1]); w.y = pk2(ya[2], ya[3]); w.z = pk2(yc[0], yc[1]); w.w = pk2(yc[2], yc[3]);
;             *(LAS u32x4*)(L + t * DA_VRS + ch * 64 + i * 16) = w;
;             if (sample_b >= 0) { float* o = p.out + OUT_GV + (size_t)(sample_b * 32 + t) * 512 + g * 128 + ch * 32 + 8 * i; *(GASP f32x4*)o = ya; *(GASP f32x4*)(o + 4) = yc; }
;         }
	v_pk_fma_f32 v[32:33], v[40:41], v[96:97], v[92:93]
	v_pk_fma_f32 v[30:31], v[38:39], v[94:95], v[90:91]
	s_waitcnt vmcnt(0)
	v_pk_fma_f32 v[40:41], v[46:47], v[100:101], v[104:105]
	v_pk_fma_f32 v[38:39], v[44:45], v[98:99], v[102:103]
	global_store_dwordx4 v[42:43], v[30:33], off
	global_store_dwordx4 v[42:43], v[38:41], off offset:16
	s_nop 0
	v_lshl_add_u64 v[90:91], s[20:21], 0, v[108:109]
	v_lshl_add_u64 v[90:91], v[90:91], 0, v[106:107]
	v_lshl_add_u64 v[74:75], v[90:91], 0, v[74:75]
	v_add_co_u32_e32 v74, vcc, s8, v74
	v_pk_mul_f32 v[90:91], v[24:25], v[0:1] op_sel_hi:[1,0]
	s_nop 0
	v_addc_co_u32_e32 v75, vcc, 0, v75, vcc
	v_pk_mul_f32 v[92:93], v[22:23], v[0:1] op_sel_hi:[1,0]
	v_sub_f32_e32 v13, v13, v110
	v_sub_f32_e32 v12, v12, v110
	v_pk_mul_f32 v[20:21], v[20:21], v[0:1] op_sel_hi:[1,0]
	v_pk_mul_f32 v[18:19], v[18:19], v[0:1] op_sel_hi:[1,0]
	v_mul_lo_u32 v59, v86, s88
	v_lshlrev_b32_e32 v77, 6, v87
	v_sub_f32_e32 v3, v3, v110
	v_sub_f32_e32 v2, v2, v110
	v_sub_f32_e32 v5, v5, v110
	v_sub_f32_e32 v4, v4, v110
	v_add3_u32 v59, 0, v59, v77
	v_sub_f32_e32 v7, v7, v110
	v_sub_f32_e32 v6, v6, v110
	v_sub_f32_e32 v9, v9, v110
	v_sub_f32_e32 v8, v8, v110
	v_pk_mul_f32 v[8:9], v[8:9], v[0:1] op_sel_hi:[1,0]
	v_pk_mul_f32 v[6:7], v[6:7], v[0:1] op_sel_hi:[1,0]
	v_pk_fma_f32 v[22:23], v[26:27], v[116:117], v[112:113]
	v_pk_fma_f32 v[24:25], v[28:29], v[118:119], v[114:115]
	v_pk_fma_f32 v[26:27], v[92:93], v[120:121], v[124:125]
	v_pk_fma_f32 v[28:29], v[90:91], v[122:123], v[126:127]
	global_store_dwordx4 v[74:75], v[22:25], off offset:32
	global_store_dwordx4 v[74:75], v[26:29], off offset:48
	v_pk_mul_f32 v[90:91], v[12:13], v[0:1] op_sel_hi:[1,0]
	v_pk_mul_f32 v[92:93], v[10:11], v[0:1] op_sel_hi:[1,0]
	v_pk_fma_f32 v[10:11], v[18:19], v[132:133], v[128:129]
	v_pk_fma_f32 v[12:13], v[20:21], v[134:135], v[130:131]
	v_pk_fma_f32 v[18:19], v[92:93], v[136:137], v[140:141]
	v_pk_fma_f32 v[20:21], v[90:91], v[138:139], v[142:143]
	global_store_dwordx4 v[74:75], v[10:13], off offset:64
	global_store_dwordx4 v[74:75], v[18:21], off offset:80
	v_pk_mul_f32 v[82:83], v[4:5], v[0:1] op_sel_hi:[1,0]
	v_pk_mul_f32 v[84:85], v[2:3], v[0:1] op_sel_hi:[1,0]
	v_cvt_pk_bf16_f32 v2, v30, v31
	v_cvt_pk_bf16_f32 v3, v32, v33
	v_cvt_pk_bf16_f32 v4, v38, v39
	v_cvt_pk_bf16_f32 v5, v40, v41
	ds_write_b128 v59, v[2:5]
	v_cvt_pk_bf16_f32 v2, v22, v23
	v_cvt_pk_bf16_f32 v3, v24, v25
	v_cvt_pk_bf16_f32 v4, v26, v27
	v_cvt_pk_bf16_f32 v5, v28, v29
	ds_write_b128 v59, v[2:5] offset:16
	v_cvt_pk_bf16_f32 v2, v10, v11
	v_cvt_pk_bf16_f32 v3, v12, v13
	v_cvt_pk_bf16_f32 v4, v18, v19
	v_cvt_pk_bf16_f32 v5, v20, v21
	ds_write_b128 v59, v[2:5] offset:32
	v_pk_fma_f32 v[2:3], v[6:7], v[148:149], v[144:145]
	v_pk_fma_f32 v[4:5], v[8:9], v[150:151], v[146:147]
	v_pk_fma_f32 v[6:7], v[84:85], v[152:153], v[156:157]
	v_pk_fma_f32 v[8:9], v[82:83], v[154:155], v[158:159]
	v_cvt_pk_bf16_f32 v10, v2, v3
	v_cvt_pk_bf16_f32 v11, v4, v5
	v_cvt_pk_bf16_f32 v12, v6, v7
	v_cvt_pk_bf16_f32 v13, v8, v9
	global_store_dwordx4 v[74:75], v[2:5], off offset:96
	ds_write_b128 v59, v[10:13] offset:48
	global_store_dwordx4 v[74:75], v[6:9], off offset:112
